# v027 + mixer SGU loop: each group's 8 ycat stores are issued after the next group's LDS-write section, so the loop-top gamma/beta wait no longer waits for store acks (in-order vmcnt)
# baseline (speedup 1.0000x reference)
.LBB0_763:
	s_waitcnt vmcnt(0)
	v_mov_b32_e32 v24, v54
	v_mov_b32_e32 v25, v56
	v_lshlrev_b32_e32 v23, 16, v147
	v_lshlrev_b32_e32 v22, 16, v146
	v_pk_add_f32 v[24:25], v[58:59], v[24:25] op_sel_hi:[0,1]
	v_mov_b32_e32 v56, v55
	v_pk_mul_f32 v[22:23], v[24:25], v[22:23]
	v_and_b32_e32 v25, 0xffff0000, v147
	v_and_b32_e32 v24, 0xffff0000, v146
	v_pk_add_f32 v[42:43], v[58:59], v[56:57] op_sel_hi:[0,1]
	v_pk_mul_f32 v[24:25], v[42:43], v[24:25]
	v_and_b32_sdwa v42, v23, v219 dst_sel:DWORD dst_unused:UNUSED_PAD src0_sel:WORD_1 src1_sel:DWORD
	v_and_b32_sdwa v43, v22, v219 dst_sel:DWORD dst_unused:UNUSED_PAD src0_sel:WORD_1 src1_sel:DWORD
	v_add3_u32 v22, v22, v43, s49
	v_add3_u32 v23, v23, v42, s49
	v_and_b32_sdwa v42, v25, v219 dst_sel:DWORD dst_unused:UNUSED_PAD src0_sel:WORD_1 src1_sel:DWORD
	v_and_b32_sdwa v43, v24, v219 dst_sel:DWORD dst_unused:UNUSED_PAD src0_sel:WORD_1 src1_sel:DWORD
	v_add3_u32 v25, v25, v42, s49
	v_add3_u32 v24, v24, v43, s49
	v_and_b32_e32 v25, 0xffff0000, v25
	v_and_b32_e32 v24, 0xffff0000, v24
	v_or_b32_sdwa v23, v25, v23 dst_sel:DWORD dst_unused:UNUSED_PAD src0_sel:DWORD src1_sel:WORD_1
	v_or_b32_sdwa v22, v24, v22 dst_sel:DWORD dst_unused:UNUSED_PAD src0_sel:DWORD src1_sel:WORD_1
	v_lshl_add_u64 v[24:25], s[56:57], 0, v[66:67]
	v_add_co_u32_e32 v24, vcc, s91, v24
	v_mov_b32_e32 v42, v50
	s_nop 0
	v_addc_co_u32_e32 v25, vcc, 0, v25, vcc
	v_mov_b32_e32 v43, v52
	v_mov_b32_e32 v230, v22
	v_mov_b32_e32 v231, v23
	v_mov_b32_e32 v246, v24
	v_mov_b32_e32 v247, v25
	v_lshlrev_b32_e32 v23, 16, v145
	v_lshlrev_b32_e32 v22, 16, v144
	v_pk_add_f32 v[42:43], v[58:59], v[42:43] op_sel_hi:[0,1]
	v_mov_b32_e32 v52, v51
	v_pk_mul_f32 v[22:23], v[42:43], v[22:23]
	v_and_b32_e32 v43, 0xffff0000, v145
	v_and_b32_e32 v42, 0xffff0000, v144
	v_pk_add_f32 v[44:45], v[58:59], v[52:53] op_sel_hi:[0,1]
	v_pk_mul_f32 v[42:43], v[44:45], v[42:43]
	v_and_b32_sdwa v44, v23, v219 dst_sel:DWORD dst_unused:UNUSED_PAD src0_sel:WORD_1 src1_sel:DWORD
	v_and_b32_sdwa v45, v22, v219 dst_sel:DWORD dst_unused:UNUSED_PAD src0_sel:WORD_1 src1_sel:DWORD
	v_add3_u32 v22, v22, v45, s49
	v_add3_u32 v23, v23, v44, s49
	v_and_b32_sdwa v44, v43, v219 dst_sel:DWORD dst_unused:UNUSED_PAD src0_sel:WORD_1 src1_sel:DWORD
	v_and_b32_sdwa v45, v42, v219 dst_sel:DWORD dst_unused:UNUSED_PAD src0_sel:WORD_1 src1_sel:DWORD
	v_add3_u32 v43, v43, v44, s49
	v_add3_u32 v42, v42, v45, s49
	v_and_b32_e32 v43, 0xffff0000, v43
	v_and_b32_e32 v42, 0xffff0000, v42
	v_or_b32_sdwa v23, v43, v23 dst_sel:DWORD dst_unused:UNUSED_PAD src0_sel:DWORD src1_sel:WORD_1
	v_or_b32_sdwa v22, v42, v22 dst_sel:DWORD dst_unused:UNUSED_PAD src0_sel:DWORD src1_sel:WORD_1
	v_mov_b32_e32 v42, v46
	v_mov_b32_e32 v43, v48
	v_mov_b32_e32 v232, v22
	v_mov_b32_e32 v233, v23
	v_lshlrev_b32_e32 v23, 16, v143
	v_lshlrev_b32_e32 v22, 16, v142
	v_pk_add_f32 v[42:43], v[58:59], v[42:43] op_sel_hi:[0,1]
	v_mov_b32_e32 v48, v47
	v_pk_mul_f32 v[22:23], v[42:43], v[22:23]
	v_and_b32_e32 v43, 0xffff0000, v143
	v_and_b32_e32 v42, 0xffff0000, v142
	v_pk_add_f32 v[44:45], v[58:59], v[48:49] op_sel_hi:[0,1]
	v_pk_mul_f32 v[42:43], v[44:45], v[42:43]
	v_and_b32_sdwa v44, v23, v219 dst_sel:DWORD dst_unused:UNUSED_PAD src0_sel:WORD_1 src1_sel:DWORD
	v_and_b32_sdwa v45, v22, v219 dst_sel:DWORD dst_unused:UNUSED_PAD src0_sel:WORD_1 src1_sel:DWORD
	v_add3_u32 v22, v22, v45, s49
	v_add3_u32 v23, v23, v44, s49
	v_and_b32_sdwa v44, v43, v219 dst_sel:DWORD dst_unused:UNUSED_PAD src0_sel:WORD_1 src1_sel:DWORD
	v_and_b32_sdwa v45, v42, v219 dst_sel:DWORD dst_unused:UNUSED_PAD src0_sel:WORD_1 src1_sel:DWORD
	v_add3_u32 v43, v43, v44, s49
	v_add3_u32 v42, v42, v45, s49
	v_and_b32_e32 v43, 0xffff0000, v43
	v_and_b32_e32 v42, 0xffff0000, v42
	v_or_b32_sdwa v23, v43, v23 dst_sel:DWORD dst_unused:UNUSED_PAD src0_sel:DWORD src1_sel:WORD_1
	v_or_b32_sdwa v22, v42, v22 dst_sel:DWORD dst_unused:UNUSED_PAD src0_sel:DWORD src1_sel:WORD_1
	v_mov_b32_e32 v42, v38
	v_mov_b32_e32 v43, v40
	v_mov_b32_e32 v234, v22
	v_mov_b32_e32 v235, v23
	v_lshlrev_b32_e32 v23, 16, v141
	v_lshlrev_b32_e32 v22, 16, v140
	v_pk_add_f32 v[42:43], v[58:59], v[42:43] op_sel_hi:[0,1]
	v_mov_b32_e32 v40, v39
	v_pk_mul_f32 v[22:23], v[42:43], v[22:23]
	v_and_b32_e32 v43, 0xffff0000, v141
	v_and_b32_e32 v42, 0xffff0000, v140
	v_pk_add_f32 v[38:39], v[58:59], v[40:41] op_sel_hi:[0,1]
	v_pk_mul_f32 v[38:39], v[38:39], v[42:43]
	v_and_b32_sdwa v40, v23, v219 dst_sel:DWORD dst_unused:UNUSED_PAD src0_sel:WORD_1 src1_sel:DWORD
	v_and_b32_sdwa v41, v22, v219 dst_sel:DWORD dst_unused:UNUSED_PAD src0_sel:WORD_1 src1_sel:DWORD
	v_add3_u32 v22, v22, v41, s49
	v_add3_u32 v23, v23, v40, s49
	v_and_b32_sdwa v40, v39, v219 dst_sel:DWORD dst_unused:UNUSED_PAD src0_sel:WORD_1 src1_sel:DWORD
	v_and_b32_sdwa v41, v38, v219 dst_sel:DWORD dst_unused:UNUSED_PAD src0_sel:WORD_1 src1_sel:DWORD
	v_add3_u32 v39, v39, v40, s49
	v_add3_u32 v38, v38, v41, s49
	v_and_b32_e32 v39, 0xffff0000, v39
	v_and_b32_e32 v38, 0xffff0000, v38
	v_or_b32_sdwa v23, v39, v23 dst_sel:DWORD dst_unused:UNUSED_PAD src0_sel:DWORD src1_sel:WORD_1
	v_or_b32_sdwa v22, v38, v22 dst_sel:DWORD dst_unused:UNUSED_PAD src0_sel:DWORD src1_sel:WORD_1
	v_mov_b32_e32 v38, v34
	v_mov_b32_e32 v39, v36
	v_mov_b32_e32 v236, v22
	v_mov_b32_e32 v237, v23
	v_lshlrev_b32_e32 v23, 16, v139
	v_lshlrev_b32_e32 v22, 16, v138
	v_pk_add_f32 v[38:39], v[58:59], v[38:39] op_sel_hi:[0,1]
	v_mov_b32_e32 v36, v35
	v_pk_mul_f32 v[22:23], v[38:39], v[22:23]
	v_and_b32_e32 v39, 0xffff0000, v139
	v_and_b32_e32 v38, 0xffff0000, v138
	v_pk_add_f32 v[34:35], v[58:59], v[36:37] op_sel_hi:[0,1]
	v_pk_mul_f32 v[34:35], v[34:35], v[38:39]
	v_and_b32_sdwa v36, v23, v219 dst_sel:DWORD dst_unused:UNUSED_PAD src0_sel:WORD_1 src1_sel:DWORD
	v_and_b32_sdwa v37, v22, v219 dst_sel:DWORD dst_unused:UNUSED_PAD src0_sel:WORD_1 src1_sel:DWORD
	v_add3_u32 v22, v22, v37, s49
	v_add3_u32 v23, v23, v36, s49
	v_and_b32_sdwa v36, v35, v219 dst_sel:DWORD dst_unused:UNUSED_PAD src0_sel:WORD_1 src1_sel:DWORD
	v_and_b32_sdwa v37, v34, v219 dst_sel:DWORD dst_unused:UNUSED_PAD src0_sel:WORD_1 src1_sel:DWORD
	v_add3_u32 v35, v35, v36, s49
	v_add3_u32 v34, v34, v37, s49
	v_and_b32_e32 v35, 0xffff0000, v35
	v_and_b32_e32 v34, 0xffff0000, v34
	v_or_b32_sdwa v23, v35, v23 dst_sel:DWORD dst_unused:UNUSED_PAD src0_sel:DWORD src1_sel:WORD_1
	v_or_b32_sdwa v22, v34, v22 dst_sel:DWORD dst_unused:UNUSED_PAD src0_sel:DWORD src1_sel:WORD_1
	v_mov_b32_e32 v34, v30
	v_mov_b32_e32 v35, v32
	v_mov_b32_e32 v238, v22
	v_mov_b32_e32 v239, v23
	v_lshlrev_b32_e32 v23, 16, v65
	v_lshlrev_b32_e32 v22, 16, v64
	v_pk_add_f32 v[34:35], v[58:59], v[34:35] op_sel_hi:[0,1]
	v_mov_b32_e32 v32, v31
	v_pk_mul_f32 v[22:23], v[34:35], v[22:23]
	v_and_b32_e32 v35, 0xffff0000, v65
	v_and_b32_e32 v34, 0xffff0000, v64
	v_pk_add_f32 v[30:31], v[58:59], v[32:33] op_sel_hi:[0,1]
	v_pk_mul_f32 v[30:31], v[30:31], v[34:35]
	v_and_b32_sdwa v32, v23, v219 dst_sel:DWORD dst_unused:UNUSED_PAD src0_sel:WORD_1 src1_sel:DWORD
	v_and_b32_sdwa v33, v22, v219 dst_sel:DWORD dst_unused:UNUSED_PAD src0_sel:WORD_1 src1_sel:DWORD
	v_add3_u32 v22, v22, v33, s49
	v_add3_u32 v23, v23, v32, s49
	v_and_b32_sdwa v32, v31, v219 dst_sel:DWORD dst_unused:UNUSED_PAD src0_sel:WORD_1 src1_sel:DWORD
	v_and_b32_sdwa v33, v30, v219 dst_sel:DWORD dst_unused:UNUSED_PAD src0_sel:WORD_1 src1_sel:DWORD
	v_add3_u32 v31, v31, v32, s49
	v_add3_u32 v30, v30, v33, s49
	v_and_b32_e32 v31, 0xffff0000, v31
	v_and_b32_e32 v30, 0xffff0000, v30
	v_or_b32_sdwa v23, v31, v23 dst_sel:DWORD dst_unused:UNUSED_PAD src0_sel:DWORD src1_sel:WORD_1
	v_or_b32_sdwa v22, v30, v22 dst_sel:DWORD dst_unused:UNUSED_PAD src0_sel:DWORD src1_sel:WORD_1
	v_mov_b32_e32 v30, v26
	v_mov_b32_e32 v31, v28
	v_mov_b32_e32 v240, v22
	v_mov_b32_e32 v241, v23
	v_lshlrev_b32_e32 v23, 16, v63
	v_lshlrev_b32_e32 v22, 16, v62
	v_pk_add_f32 v[30:31], v[58:59], v[30:31] op_sel_hi:[0,1]
	v_mov_b32_e32 v28, v27
	v_pk_mul_f32 v[22:23], v[30:31], v[22:23]
	v_and_b32_e32 v31, 0xffff0000, v63
	v_and_b32_e32 v30, 0xffff0000, v62
	v_pk_add_f32 v[26:27], v[58:59], v[28:29] op_sel_hi:[0,1]
	v_pk_mul_f32 v[26:27], v[26:27], v[30:31]
	v_and_b32_sdwa v28, v23, v219 dst_sel:DWORD dst_unused:UNUSED_PAD src0_sel:WORD_1 src1_sel:DWORD
	v_and_b32_sdwa v29, v22, v219 dst_sel:DWORD dst_unused:UNUSED_PAD src0_sel:WORD_1 src1_sel:DWORD
	v_add3_u32 v22, v22, v29, s49
	v_add3_u32 v23, v23, v28, s49
	v_and_b32_sdwa v28, v27, v219 dst_sel:DWORD dst_unused:UNUSED_PAD src0_sel:WORD_1 src1_sel:DWORD
	v_and_b32_sdwa v29, v26, v219 dst_sel:DWORD dst_unused:UNUSED_PAD src0_sel:WORD_1 src1_sel:DWORD
	v_add3_u32 v27, v27, v28, s49
	v_add3_u32 v26, v26, v29, s49
	v_and_b32_e32 v27, 0xffff0000, v27
	v_and_b32_e32 v26, 0xffff0000, v26
	v_or_b32_sdwa v23, v27, v23 dst_sel:DWORD dst_unused:UNUSED_PAD src0_sel:DWORD src1_sel:WORD_1
	v_or_b32_sdwa v22, v26, v22 dst_sel:DWORD dst_unused:UNUSED_PAD src0_sel:DWORD src1_sel:WORD_1
	v_mov_b32_e32 v26, v18
	v_mov_b32_e32 v27, v20
	v_mov_b32_e32 v242, v22
	v_mov_b32_e32 v243, v23
	v_lshlrev_b32_e32 v23, 16, v61
	v_lshlrev_b32_e32 v22, 16, v60
	v_pk_add_f32 v[26:27], v[58:59], v[26:27] op_sel_hi:[0,1]
	v_mov_b32_e32 v20, v19
	v_pk_mul_f32 v[22:23], v[26:27], v[22:23]
	v_and_b32_e32 v27, 0xffff0000, v61
	v_and_b32_e32 v26, 0xffff0000, v60
	v_pk_add_f32 v[18:19], v[58:59], v[20:21] op_sel_hi:[0,1]
	v_pk_mul_f32 v[18:19], v[18:19], v[26:27]
	v_and_b32_sdwa v20, v23, v219 dst_sel:DWORD dst_unused:UNUSED_PAD src0_sel:WORD_1 src1_sel:DWORD
	v_and_b32_sdwa v21, v22, v219 dst_sel:DWORD dst_unused:UNUSED_PAD src0_sel:WORD_1 src1_sel:DWORD
	v_add3_u32 v21, v22, v21, s49
	v_add3_u32 v20, v23, v20, s49
	v_and_b32_sdwa v22, v19, v219 dst_sel:DWORD dst_unused:UNUSED_PAD src0_sel:WORD_1 src1_sel:DWORD
	v_and_b32_sdwa v23, v18, v219 dst_sel:DWORD dst_unused:UNUSED_PAD src0_sel:WORD_1 src1_sel:DWORD
	s_add_i32 s11, s11, 1
	v_add3_u32 v19, v19, v22, s49
	v_add3_u32 v18, v18, v23, s49
	s_add_u32 s8, s8, 0x200
	v_and_b32_e32 v19, 0xffff0000, v19
	v_and_b32_e32 v18, 0xffff0000, v18
	s_addc_u32 s9, s9, 0
	s_mov_b64 s[6:7], 0x8000
	v_or_b32_sdwa v19, v19, v20 dst_sel:DWORD dst_unused:UNUSED_PAD src0_sel:DWORD src1_sel:WORD_1
	v_or_b32_sdwa v18, v18, v21 dst_sel:DWORD dst_unused:UNUSED_PAD src0_sel:DWORD src1_sel:WORD_1
	v_lshl_add_u64 v[66:67], v[66:67], 0, s[94:95]
	v_lshl_add_u64 v[70:71], v[70:71], 0, s[94:95]
	v_lshl_add_u64 v[72:73], v[72:73], 0, s[6:7]
	s_cmpk_eq_i32 s8, 0x800
	v_lshl_add_u64 v[130:131], v[130:131], 0, s[94:95]
	v_mov_b32_e32 v244, v18
	v_mov_b32_e32 v245, v19
	s_cbranch_scc1 .LBB0_770

.LBB0_766:
	s_cmp_eq_u32 s11, 0
	s_cbranch_scc1 .Lmixdef_skip
	global_store_dwordx2 v[246:247], v[230:231], off
	global_store_dwordx2 v[246:247], v[232:233], off offset:32
	global_store_dwordx2 v[246:247], v[234:235], off offset:64
	global_store_dwordx2 v[246:247], v[236:237], off offset:96
	global_store_dwordx2 v[246:247], v[238:239], off offset:128
	global_store_dwordx2 v[246:247], v[240:241], off offset:160
	global_store_dwordx2 v[246:247], v[242:243], off offset:192
	global_store_dwordx2 v[246:247], v[244:245], off offset:224

.LBB0_770:
	global_store_dwordx2 v[246:247], v[230:231], off
	global_store_dwordx2 v[246:247], v[232:233], off offset:32
	global_store_dwordx2 v[246:247], v[234:235], off offset:64
	global_store_dwordx2 v[246:247], v[236:237], off offset:96
	global_store_dwordx2 v[246:247], v[238:239], off offset:128
	global_store_dwordx2 v[246:247], v[240:241], off offset:160
	global_store_dwordx2 v[246:247], v[242:243], off offset:192
	global_store_dwordx2 v[246:247], v[244:245], off offset:224
	s_waitcnt lgkmcnt(0)
	s_cmp_lg_u32 s10, 0
	s_mov_b64 s[6:7], -1
	s_barrier
	s_cbranch_scc0 .LBB0_856
	v_add_u32_e32 v4, s66, v225
	v_ashrrev_i32_e32 v2, 31, v4
	v_lshrrev_b32_e32 v2, 20, v2
	v_add_u32_e32 v2, v4, v2
	v_and_b32_e32 v2, 0xfffff000, v2
	v_sub_u32_e32 v146, v4, v2
	v_mov_b64_e32 v[2:3], s[58:59]
	v_mad_i64_i32 v[2:3], s[6:7], v4, s97, v[2:3]
	v_mov_b32_e32 v127, v163
	v_lshl_add_u64 v[2:3], v[2:3], 0, v[126:127]
	s_mov_b64 s[6:7], 0x1c00
	v_lshl_add_u64 v[68:69], v[2:3], 0, s[6:7]
	v_mov_b32_e32 v12, 0
	v_cmp_lt_i32_e64 s[12:13], 0, v146
	v_mov_b32_e32 v16, 0
	v_mov_b32_e32 v17, 0
	v_mov_b32_e32 v18, 0
	v_mov_b32_e32 v19, 0
	s_and_saveexec_b64 s[6:7], s[12:13]
	s_cbranch_execz .LBB0_773
	v_add_co_u32_e32 v2, vcc, 0xffffd000, v68
	s_nop 1
	v_addc_co_u32_e32 v3, vcc, -1, v69, vcc
	global_load_dwordx4 v[16:19], v[2:3], off offset:-2048
